# next-tile V fragment reads moved into the MFMA phase tail, first-MFMA LDS wait relaxed
# baseline (speedup 1.0000x reference)
; #define LAS3 __attribute__((address_space(3)))
; #define ATT_BAR_V(full) do { if (full) { if (MODE) ATT_WAIT_BAR(4); else ATT_WAIT_BAR(2); } else ATT_WAIT_BAR(0); } while (0)
; #define ATT_BAR_L() asm volatile("s_waitcnt lgkmcnt(0)\n\ts_barrier" ::: "memory")
; #define ATT_SB() __builtin_amdgcn_sched_barrier(0)
; template <int MODE>
; __device__ __forceinline__ void attn_unit(const Tensors& T0, int ureq, int b, int hh, int qblk, LAS3 char* shm, const bool dummy = false) {
;     ...
;     if (!(ATT_ABL == 4 && dummy)) { const int kso = (i & 3) * SLOTB; const int vp = ((i - 1) & 3) * SLOTB;
;       bf16x8 kf[8];
; #pragma unroll
;       for (int d0 = 0; d0 < 2; ++d0) { kf[2 * d0] = *(const LAS3 bf16x8*)(kp[d0] + kso); kf[2 * d0 + 1] = *(const LAS3 bf16x8*)(kp[d0] + kso + 4096); }
;       if (i > 0) { ATT_VREAD(vB, 1, vp); }
;       ATT_SB();
;       if (i > 0) { ATT_PVK_RD(vA, 0, vp); }
;       C0 = __builtin_amdgcn_mfma_f32_32x32x16_bf16(kf[0], qr[0], negm, 0, 0, 0); C1 = __builtin_amdgcn_mfma_f32_32x32x16_bf16(kf[1], qr[0], negm, 0, 0, 0);
;       C0 = __builtin_amdgcn_mfma_f32_32x32x16_bf16(kf[2], qr[1], C0, 0, 0, 0); C1 = __builtin_amdgcn_mfma_f32_32x32x16_bf16(kf[3], qr[1], C1, 0, 0, 0);
;       ATT_SB();
; #pragma unroll
;       for (int d0 = 2; d0 < 4; ++d0) { kf[2 * d0] = *(const LAS3 bf16x8*)(kp[d0] + kso); kf[2 * d0 + 1] = *(const LAS3 bf16x8*)(kp[d0] + kso + 4096); }
;       ATT_SB();
;       if (i > 0) { ATT_PVK_RD(vB, 1, vp); }
; #pragma unroll
;       for (int d0 = 2; d0 < 4; ++d0) { C0 = __builtin_amdgcn_mfma_f32_32x32x16_bf16(kf[2 * d0], qr[d0], C0, 0, 0, 0); C1 = __builtin_amdgcn_mfma_f32_32x32x16_bf16(kf[2 * d0 + 1], qr[d0], C1, 0, 0, 0); }
;       ATT_SB();
;       if (i > 0) { ATT_PVK(vA, 2); ATT_PVK(vB, 3); } }
;     asm volatile("" : "+v"(C0), "+v"(C1));
; #pragma unroll
;     for (int d = 0; d < ND; ++d) asm volatile("" : "+v"(o[d]));
;     if (grp == 0) ATT_BAR_L(); else ATT_BAR_V(i + 2 < NT);
;     if (i == 0) asm volatile("s_nop 15\n\ts_nop 7" : "+v"(C0), "+v"(C1));
;     else asm volatile("" : "+v"(C0), "+v"(C1));
;     ATT_VREAD(vA, 0, (i & 3) * SLOTB); ATT_SB();
;     if (grp == 0 && i + 2 < NT && !(ATT_ABL == 2 && dummy)) ATT_DMA(t + 2, ((i + 2) & 3) * SLOTB);
;     if (grp == 1 && i + 3 < NT && !(ATT_ABL == 2 && dummy)) ATT_DMA(t + 3, ((i + 3) & 3) * SLOTB);
.Lm1_negm_keep:
	ds_read_b128 v[100:103], v104
	ds_read_b128 v[206:209], v104 offset:4096
	v_add_u32_e32 v104, s18, v195
	v_add_u32_e32 v205, s99, v193
	v_add_u32_e32 v242, s99, v190
	v_add_u32_e32 v248, s18, v193
	v_add_u32_e32 v249, s18, v190
	ds_read_b128 v[210:213], v104
	ds_read_b128 v[214:217], v104 offset:4096
	ds_read_b64_tr_b16 v[218:219], v205 offset:18432
	ds_read_b64_tr_b16 v[220:221], v205 offset:19456
	ds_read_b64_tr_b16 v[222:223], v242 offset:18432
	ds_read_b64_tr_b16 v[224:225], v242 offset:19456
	ds_read_b64_tr_b16 v[226:227], v205 offset:26624
	ds_read_b64_tr_b16 v[228:229], v205 offset:27648
	ds_read_b64_tr_b16 v[230:231], v242 offset:26624
	ds_read_b64_tr_b16 v[232:233], v242 offset:27648
	v_mfma_f32_32x32x16_bf16 v[48:63], v[96:99], v[156:159], v[48:63]
	ds_read_b64_tr_b16 v[156:157], v205 offset:20480
	ds_read_b64_tr_b16 v[158:159], v205 offset:21504
	v_mfma_f32_32x32x16_bf16 v[64:79], v[96:99], v[152:155], v[64:79]
	ds_read_b64_tr_b16 v[152:153], v242 offset:20480
	ds_read_b64_tr_b16 v[154:155], v242 offset:21504
	v_mfma_f32_32x32x16_bf16 v[32:47], v[96:99], v[148:151], v[32:47]
	ds_read_b64_tr_b16 v[148:149], v205 offset:28672
	ds_read_b64_tr_b16 v[150:151], v205 offset:29696
	v_mfma_f32_32x32x16_bf16 v[16:31], v[96:99], v[144:147], v[16:31]
	ds_read_b64_tr_b16 v[144:145], v242 offset:28672
	ds_read_b64_tr_b16 v[146:147], v242 offset:29696
	s_waitcnt lgkmcnt(15)
	v_mfma_f32_32x32x16_bf16 v[112:127], v[100:103], v[128:131], v[80:95]
	v_add_u32_e32 v238, s18, v197
	v_mfma_f32_32x32x16_bf16 v[96:111], v[206:209], v[128:131], v[80:95]
	v_mfma_f32_32x32x16_bf16 v[112:127], v[210:213], v[132:135], v[112:127]
	v_add_u32_e32 v210, s18, v196
	ds_read_b128 v[206:209], v210
	ds_read_b128 v[210:213], v210 offset:4096
	ds_read_b128 v[234:237], v238
	ds_read_b128 v[238:241], v238 offset:4096
	v_mfma_f32_32x32x16_bf16 v[96:111], v[214:217], v[132:135], v[96:111]
	s_waitcnt lgkmcnt(14)
	v_mfma_f32_32x32x16_bf16 v[48:63], v[168:171], v[218:221], v[48:63]
	ds_read_b64_tr_b16 v[214:215], v205 offset:22528
	ds_read_b64_tr_b16 v[216:217], v205 offset:23552
	v_mfma_f32_32x32x16_bf16 v[64:79], v[168:171], v[222:225], v[64:79]
	ds_read_b64_tr_b16 v[218:219], v242 offset:22528
	ds_read_b64_tr_b16 v[220:221], v242 offset:23552
	v_mfma_f32_32x32x16_bf16 v[32:47], v[168:171], v[226:229], v[32:47]
	ds_read_b64_tr_b16 v[222:223], v205 offset:30720
	ds_read_b64_tr_b16 v[224:225], v205 offset:31744
	s_waitcnt lgkmcnt(14)
	v_mfma_f32_32x32x16_bf16 v[16:31], v[168:171], v[230:233], v[16:31]
	ds_read_b64_tr_b16 v[168:169], v242 offset:30720
	ds_read_b64_tr_b16 v[170:171], v242 offset:31744
	s_waitcnt lgkmcnt(11)
	v_mfma_f32_32x32x16_bf16 v[112:127], v[206:209], v[136:139], v[112:127]
	s_waitcnt lgkmcnt(10)
	v_mfma_f32_32x32x16_bf16 v[96:111], v[210:213], v[136:139], v[96:111]
	s_waitcnt lgkmcnt(9)
	v_mfma_f32_32x32x16_bf16 v[112:127], v[234:237], v[140:143], v[112:127]
	s_waitcnt lgkmcnt(8)
	v_mfma_f32_32x32x16_bf16 v[96:111], v[238:241], v[140:143], v[96:111]
	v_mfma_f32_32x32x16_bf16 v[48:63], v[164:167], v[156:159], v[48:63]
	ds_read_b64_tr_b16 v[156:157], v248 offset:16384
	ds_read_b64_tr_b16 v[158:159], v248 offset:17408
	v_mfma_f32_32x32x16_bf16 v[64:79], v[164:167], v[152:155], v[64:79]
	ds_read_b64_tr_b16 v[152:153], v249 offset:16384
	ds_read_b64_tr_b16 v[154:155], v249 offset:17408
	v_mfma_f32_32x32x16_bf16 v[32:47], v[164:167], v[148:151], v[32:47]
	ds_read_b64_tr_b16 v[148:149], v248 offset:24576
	ds_read_b64_tr_b16 v[150:151], v248 offset:25600
	v_mfma_f32_32x32x16_bf16 v[16:31], v[164:167], v[144:147], v[16:31]
	ds_read_b64_tr_b16 v[144:145], v249 offset:24576
	ds_read_b64_tr_b16 v[146:147], v249 offset:25600
	s_waitcnt lgkmcnt(14)
	v_mfma_f32_32x32x16_bf16 v[48:63], v[160:163], v[214:217], v[48:63]
	s_waitcnt lgkmcnt(12)
	v_mfma_f32_32x32x16_bf16 v[64:79], v[160:163], v[218:221], v[64:79]
	s_waitcnt lgkmcnt(10)
	v_mfma_f32_32x32x16_bf16 v[32:47], v[160:163], v[222:225], v[32:47]
	s_waitcnt lgkmcnt(8)
	v_mfma_f32_32x32x16_bf16 v[16:31], v[160:163], v[168:171], v[16:31]
	s_waitcnt lgkmcnt(0)
	s_barrier
.LBB0_113:
	s_setprio 0
	s_cmp_ge_u32 s96, s82
	s_cbranch_scc1 .Lm1_nodma_g0
	s_and_b32 s18, s98, 0x18000
	s_add_i32 s18, s18, s92
	s_mov_b32 m0, s18
	s_add_i32 s19, s18, 0x2000
	global_load_lds_dwordx4 v244, s[100:101]
	s_mov_b32 m0, s19
	s_add_i32 s19, s18, 0x4000
	global_load_lds_dwordx4 v245, s[100:101]
	s_mov_b32 m0, s19
	s_add_i32 s19, s18, 0x6000
	global_load_lds_dwordx4 v246, s[100:101]
	s_mov_b32 m0, s19
	s_nop 0
	global_load_lds_dwordx4 v247, s[100:101]

; #define LAS3 __attribute__((address_space(3)))
; #define ATT_BAR_V(full) do { if (full) { if (MODE) ATT_WAIT_BAR(4); else ATT_WAIT_BAR(2); } else ATT_WAIT_BAR(0); } while (0)
; #define ATT_BAR_L() asm volatile("s_waitcnt lgkmcnt(0)\n\ts_barrier" ::: "memory")
; #define ATT_SB() __builtin_amdgcn_sched_barrier(0)
; template <int MODE>
; __device__ __forceinline__ void attn_unit(const Tensors& T0, int ureq, int b, int hh, int qblk, LAS3 char* shm, const bool dummy = false) {
;     ...
;     if (!(ATT_ABL == 4 && dummy)) { const int kso = (i & 3) * SLOTB; const int vp = ((i - 1) & 3) * SLOTB;
;       bf16x8 kf[8];
; #pragma unroll
;       for (int d0 = 0; d0 < 2; ++d0) { kf[2 * d0] = *(const LAS3 bf16x8*)(kp[d0] + kso); kf[2 * d0 + 1] = *(const LAS3 bf16x8*)(kp[d0] + kso + 4096); }
;       if (i > 0) { ATT_VREAD(vB, 1, vp); }
;       ATT_SB();
;       if (i > 0) { ATT_PVK_RD(vA, 0, vp); }
;       C0 = __builtin_amdgcn_mfma_f32_32x32x16_bf16(kf[0], qr[0], negm, 0, 0, 0); C1 = __builtin_amdgcn_mfma_f32_32x32x16_bf16(kf[1], qr[0], negm, 0, 0, 0);
;       C0 = __builtin_amdgcn_mfma_f32_32x32x16_bf16(kf[2], qr[1], C0, 0, 0, 0); C1 = __builtin_amdgcn_mfma_f32_32x32x16_bf16(kf[3], qr[1], C1, 0, 0, 0);
;       ATT_SB();
; #pragma unroll
;       for (int d0 = 2; d0 < 4; ++d0) { kf[2 * d0] = *(const LAS3 bf16x8*)(kp[d0] + kso); kf[2 * d0 + 1] = *(const LAS3 bf16x8*)(kp[d0] + kso + 4096); }
;       ATT_SB();
;       if (i > 0) { ATT_PVK_RD(vB, 1, vp); }
; #pragma unroll
;       for (int d0 = 2; d0 < 4; ++d0) { C0 = __builtin_amdgcn_mfma_f32_32x32x16_bf16(kf[2 * d0], qr[d0], C0, 0, 0, 0); C1 = __builtin_amdgcn_mfma_f32_32x32x16_bf16(kf[2 * d0 + 1], qr[d0], C1, 0, 0, 0); }
;       ATT_SB();
;       if (i > 0) { ATT_PVK(vA, 2); ATT_PVK(vB, 3); } }
;     asm volatile("" : "+v"(C0), "+v"(C1));
; #pragma unroll
;     for (int d = 0; d < ND; ++d) asm volatile("" : "+v"(o[d]));
;     if (grp == 0) ATT_BAR_L(); else ATT_BAR_V(i + 2 < NT);
;     if (i == 0) asm volatile("s_nop 15\n\ts_nop 7" : "+v"(C0), "+v"(C1));
;     else asm volatile("" : "+v"(C0), "+v"(C1));
;     ATT_VREAD(vA, 0, (i & 3) * SLOTB); ATT_SB();
;     if (grp == 0 && i + 2 < NT && !(ATT_ABL == 2 && dummy)) ATT_DMA(t + 2, ((i + 2) & 3) * SLOTB);
;     if (grp == 1 && i + 3 < NT && !(ATT_ABL == 2 && dummy)) ATT_DMA(t + 3, ((i + 3) & 3) * SLOTB);
.Lm1g1_negm_keep:
	ds_read_b128 v[100:103], v104
	ds_read_b128 v[206:209], v104 offset:4096
	v_add_u32_e32 v104, s18, v195
	v_add_u32_e32 v205, s99, v193
	v_add_u32_e32 v242, s99, v190
	v_add_u32_e32 v248, s18, v193
	v_add_u32_e32 v249, s18, v190
	ds_read_b128 v[210:213], v104
	ds_read_b128 v[214:217], v104 offset:4096
	ds_read_b64_tr_b16 v[218:219], v205 offset:18432
	ds_read_b64_tr_b16 v[220:221], v205 offset:19456
	ds_read_b64_tr_b16 v[222:223], v242 offset:18432
	ds_read_b64_tr_b16 v[224:225], v242 offset:19456
	ds_read_b64_tr_b16 v[226:227], v205 offset:26624
	ds_read_b64_tr_b16 v[228:229], v205 offset:27648
	ds_read_b64_tr_b16 v[230:231], v242 offset:26624
	ds_read_b64_tr_b16 v[232:233], v242 offset:27648
	v_mfma_f32_32x32x16_bf16 v[48:63], v[96:99], v[156:159], v[48:63]
	ds_read_b64_tr_b16 v[156:157], v205 offset:20480
	ds_read_b64_tr_b16 v[158:159], v205 offset:21504
	v_mfma_f32_32x32x16_bf16 v[64:79], v[96:99], v[152:155], v[64:79]
	ds_read_b64_tr_b16 v[152:153], v242 offset:20480
	ds_read_b64_tr_b16 v[154:155], v242 offset:21504
	v_mfma_f32_32x32x16_bf16 v[32:47], v[96:99], v[148:151], v[32:47]
	ds_read_b64_tr_b16 v[148:149], v205 offset:28672
	ds_read_b64_tr_b16 v[150:151], v205 offset:29696
	v_mfma_f32_32x32x16_bf16 v[16:31], v[96:99], v[144:147], v[16:31]
	ds_read_b64_tr_b16 v[144:145], v242 offset:28672
	ds_read_b64_tr_b16 v[146:147], v242 offset:29696
	s_waitcnt lgkmcnt(15)
	v_mfma_f32_32x32x16_bf16 v[112:127], v[100:103], v[128:131], v[80:95]
	v_add_u32_e32 v238, s18, v197
	v_mfma_f32_32x32x16_bf16 v[96:111], v[206:209], v[128:131], v[80:95]
	v_mfma_f32_32x32x16_bf16 v[112:127], v[210:213], v[132:135], v[112:127]
	v_add_u32_e32 v210, s18, v196
	ds_read_b128 v[206:209], v210
	ds_read_b128 v[210:213], v210 offset:4096
	ds_read_b128 v[234:237], v238
	ds_read_b128 v[238:241], v238 offset:4096
	v_mfma_f32_32x32x16_bf16 v[96:111], v[214:217], v[132:135], v[96:111]
	s_waitcnt lgkmcnt(14)
	v_mfma_f32_32x32x16_bf16 v[48:63], v[168:171], v[218:221], v[48:63]
	ds_read_b64_tr_b16 v[214:215], v205 offset:22528
	ds_read_b64_tr_b16 v[216:217], v205 offset:23552
	v_mfma_f32_32x32x16_bf16 v[64:79], v[168:171], v[222:225], v[64:79]
	ds_read_b64_tr_b16 v[218:219], v242 offset:22528
	ds_read_b64_tr_b16 v[220:221], v242 offset:23552
	v_mfma_f32_32x32x16_bf16 v[32:47], v[168:171], v[226:229], v[32:47]
	ds_read_b64_tr_b16 v[222:223], v205 offset:30720
	ds_read_b64_tr_b16 v[224:225], v205 offset:31744
	s_waitcnt lgkmcnt(14)
	v_mfma_f32_32x32x16_bf16 v[16:31], v[168:171], v[230:233], v[16:31]
	ds_read_b64_tr_b16 v[168:169], v242 offset:30720
	ds_read_b64_tr_b16 v[170:171], v242 offset:31744
	s_waitcnt lgkmcnt(11)
	v_mfma_f32_32x32x16_bf16 v[112:127], v[206:209], v[136:139], v[112:127]
	s_waitcnt lgkmcnt(10)
	v_mfma_f32_32x32x16_bf16 v[96:111], v[210:213], v[136:139], v[96:111]
	s_waitcnt lgkmcnt(9)
	v_mfma_f32_32x32x16_bf16 v[112:127], v[234:237], v[140:143], v[112:127]
	s_waitcnt lgkmcnt(8)
	v_mfma_f32_32x32x16_bf16 v[96:111], v[238:241], v[140:143], v[96:111]
	v_mfma_f32_32x32x16_bf16 v[48:63], v[164:167], v[156:159], v[48:63]
	ds_read_b64_tr_b16 v[156:157], v248 offset:16384
	ds_read_b64_tr_b16 v[158:159], v248 offset:17408
	v_mfma_f32_32x32x16_bf16 v[64:79], v[164:167], v[152:155], v[64:79]
	ds_read_b64_tr_b16 v[152:153], v249 offset:16384
	ds_read_b64_tr_b16 v[154:155], v249 offset:17408
	v_mfma_f32_32x32x16_bf16 v[32:47], v[164:167], v[148:151], v[32:47]
	ds_read_b64_tr_b16 v[148:149], v248 offset:24576
	ds_read_b64_tr_b16 v[150:151], v248 offset:25600
	v_mfma_f32_32x32x16_bf16 v[16:31], v[164:167], v[144:147], v[16:31]
	ds_read_b64_tr_b16 v[144:145], v249 offset:24576
	ds_read_b64_tr_b16 v[146:147], v249 offset:25600
	s_waitcnt lgkmcnt(14)
	v_mfma_f32_32x32x16_bf16 v[48:63], v[160:163], v[214:217], v[48:63]
	s_waitcnt lgkmcnt(12)
	v_mfma_f32_32x32x16_bf16 v[64:79], v[160:163], v[218:221], v[64:79]
	s_waitcnt lgkmcnt(10)
	v_mfma_f32_32x32x16_bf16 v[32:47], v[160:163], v[222:225], v[32:47]
	s_waitcnt lgkmcnt(8)
	v_mfma_f32_32x32x16_bf16 v[16:31], v[160:163], v[168:171], v[16:31]
	s_cmp_ge_u32 s96, s82
	s_cbranch_scc1 .Lm1_A_drain_g1
	s_waitcnt vmcnt(4) lgkmcnt(0)
	s_barrier
.Lm1_A_done_g1:
.Lm1g1_113:
	s_setprio 0
	s_cmp_ge_u32 s93, s83
	s_cbranch_scc1 .Lm1_nodma_g1
	s_add_i32 s18, s99, s92
	s_mov_b32 m0, s18
	s_add_i32 s19, s18, 0x2000
	global_load_lds_dwordx4 v244, s[100:101]
	s_mov_b32 m0, s19
	s_add_i32 s19, s18, 0x4000
	global_load_lds_dwordx4 v245, s[100:101]
	s_mov_b32 m0, s19
	s_add_i32 s19, s18, 0x6000
	global_load_lds_dwordx4 v246, s[100:101]
	s_mov_b32 m0, s19
	s_nop 0
	global_load_lds_dwordx4 v247, s[100:101]

; __global__ void __launch_bounds__(NWAVES * 64, 2) mixer_fwd(Args args) {
	.amdhsa_kernel _Z9mixer_fwd4Args
		.amdhsa_group_segment_fixed_size 0
		.amdhsa_private_segment_fixed_size 0
		.amdhsa_kernarg_size 376
		.amdhsa_user_sgpr_count 2
		.amdhsa_user_sgpr_dispatch_ptr 0
		.amdhsa_user_sgpr_queue_ptr 0
		.amdhsa_user_sgpr_kernarg_segment_ptr 1
		.amdhsa_user_sgpr_dispatch_id 0
		.amdhsa_user_sgpr_kernarg_preload_length 0
		.amdhsa_user_sgpr_kernarg_preload_offset 0
		.amdhsa_user_sgpr_private_segment_size 0
		.amdhsa_uses_dynamic_stack 0
		.amdhsa_enable_private_segment 0
		.amdhsa_system_sgpr_workgroup_id_x 1
		.amdhsa_system_sgpr_workgroup_id_y 0
		.amdhsa_system_sgpr_workgroup_id_z 0
		.amdhsa_system_sgpr_workgroup_info 0
		.amdhsa_system_vgpr_workitem_id 2
		.amdhsa_next_free_vgpr 256
		.amdhsa_next_free_sgpr 102
		.amdhsa_accum_offset 256
		.amdhsa_reserve_vcc 1
		.amdhsa_float_round_mode_32 0
		.amdhsa_float_round_mode_16_64 0
		.amdhsa_float_denorm_mode_32 3
		.amdhsa_float_denorm_mode_16_64 3
		.amdhsa_dx10_clamp 1
		.amdhsa_ieee_mode 1
		.amdhsa_fp16_overflow 0
		.amdhsa_tg_split 0
		.amdhsa_exception_fp_ieee_invalid_op 0
		.amdhsa_exception_fp_denorm_src 0
		.amdhsa_exception_fp_ieee_div_zero 0
		.amdhsa_exception_fp_ieee_overflow 0
		.amdhsa_exception_fp_ieee_underflow 0
		.amdhsa_exception_fp_ieee_inexact 0
		.amdhsa_exception_int_div_zero 0
	.end_amdhsa_kernel

; __global__ void __launch_bounds__(NWAVES * 64, 2) mixer_fwd(Args args) {
amdhsa.kernels:
  - .agpr_count:     0
    .args:
      - .offset:         0
        .size:           120
        .value_kind:     by_value
      - .offset:         120
        .size:           4
        .value_kind:     hidden_block_count_x
      - .offset:         124
        .size:           4
        .value_kind:     hidden_block_count_y
      - .offset:         128
        .size:           4
        .value_kind:     hidden_block_count_z
      - .offset:         132
        .size:           2
        .value_kind:     hidden_group_size_x
      - .offset:         134
        .size:           2
        .value_kind:     hidden_group_size_y
      - .offset:         136
        .size:           2
        .value_kind:     hidden_group_size_z
      - .offset:         138
        .size:           2
        .value_kind:     hidden_remainder_x
      - .offset:         140
        .size:           2
        .value_kind:     hidden_remainder_y
      - .offset:         142
        .size:           2
        .value_kind:     hidden_remainder_z
      - .offset:         160
        .size:           8
        .value_kind:     hidden_global_offset_x
      - .offset:         168
        .size:           8
        .value_kind:     hidden_global_offset_y
      - .offset:         176
        .size:           8
        .value_kind:     hidden_global_offset_z
      - .offset:         184
        .size:           2
        .value_kind:     hidden_grid_dims
      - .offset:         208
        .size:           8
        .value_kind:     hidden_multigrid_sync_arg
      - .offset:         240
        .size:           4
        .value_kind:     hidden_dynamic_lds_size
    .group_segment_fixed_size: 0
    .kernarg_segment_align: 8
    .kernarg_segment_size: 376
    .language:       OpenCL C
    .language_version:
      - 2
      - 0
    .max_flat_workgroup_size: 512
    .name:           _Z9mixer_fwd4Args
    .private_segment_fixed_size: 0
    .sgpr_count:     108
    .sgpr_spill_count: 2
    .symbol:         _Z9mixer_fwd4Args.kd
    .uniform_work_group_size: 1
    .uses_dynamic_stack: false
    .vgpr_count:     256
    .vgpr_spill_count: 0
    .wavefront_size: 64
